# v68 + attention: Q-rope table used in place (16 v_mov removed), softmax max subtraction in place with v_pk_add_f32 (33 VALU fewer per tile); bit-identical
# speedup vs baseline: 1.0102x; 1.0102x over previous
.LBB0_578:
	v_or_b32_e32 v16, 0x100, v80
	v_cmp_le_u32_e32 vcc, v80, v149
	v_cmp_gt_u32_e64 s[0:1], s61, v16
	s_and_b64 vcc, vcc, s[0:1]
	v_mul_f32_e32 v12, 0x3e38aa3b, v12
	v_or_b32_e32 v16, 0x104, v80
	v_cndmask_b32_e32 v12, v208, v12, vcc
	v_cmp_le_u32_e32 vcc, v16, v51
	v_cmp_gt_u32_e64 s[0:1], s61, v16
	s_and_b64 vcc, vcc, s[0:1]
	v_mul_f32_e32 v8, 0x3e38aa3b, v8
	v_or_b32_e32 v17, 0x101, v80
	v_cndmask_b32_e32 v8, v208, v8, vcc
	v_cmp_le_u32_e32 vcc, v17, v51
	v_cmp_gt_u32_e64 s[0:1], s61, v17
	s_and_b64 vcc, vcc, s[0:1]
	v_mul_f32_e32 v13, 0x3e38aa3b, v13
	v_or_b32_e32 v17, 0x105, v80
	v_cndmask_b32_e32 v13, v208, v13, vcc
	v_cmp_le_u32_e32 vcc, v17, v51
	v_cmp_gt_u32_e64 s[0:1], s61, v17
	s_and_b64 vcc, vcc, s[0:1]
	v_mul_f32_e32 v9, 0x3e38aa3b, v9
	v_cndmask_b32_e32 v149, v208, v9, vcc
	v_max_f32_e32 v16, v12, v8
	v_max_f32_e32 v9, v13, v149
	v_max3_f32 v9, v151, v16, v9
	v_or_b32_e32 v16, 0x102, v80
	v_cmp_le_u32_e32 vcc, v16, v51
	v_cmp_gt_u32_e64 s[0:1], s61, v16
	s_and_b64 vcc, vcc, s[0:1]
	v_mul_f32_e32 v14, 0x3e38aa3b, v14
	v_or_b32_e32 v16, 0x106, v80
	v_cndmask_b32_e32 v14, v208, v14, vcc
	v_cmp_le_u32_e32 vcc, v16, v51
	v_cmp_gt_u32_e64 s[0:1], s61, v16
	s_and_b64 vcc, vcc, s[0:1]
	v_mul_f32_e32 v10, 0x3e38aa3b, v10
	v_or_b32_e32 v16, 0x103, v80
	v_cndmask_b32_e32 v151, v208, v10, vcc
	v_cmp_le_u32_e32 vcc, v16, v51
	v_cmp_gt_u32_e64 s[0:1], s61, v16
	s_and_b64 vcc, vcc, s[0:1]
	v_mul_f32_e32 v15, 0x3e38aa3b, v15
	v_cndmask_b32_e32 v152, v208, v15, vcc
	v_or_b32_e32 v15, 0x107, v80
	v_cmp_le_u32_e32 vcc, v15, v51
	v_cmp_gt_u32_e64 s[0:1], s61, v15
	s_and_b64 vcc, vcc, s[0:1]
	v_mul_f32_e32 v11, 0x3e38aa3b, v11
	v_cndmask_b32_e32 v173, v208, v11, vcc
	v_max_f32_e32 v10, v14, v151
	v_max_f32_e32 v11, v152, v173
	v_max3_f32 v9, v9, v10, v11
	ds_bpermute_b32 v10, v114, v9
	s_waitcnt lgkmcnt(0)
	v_max_f32_e32 v10, v10, v10
	v_max_f32_e32 v9, v9, v10
	ds_bpermute_b32 v10, v117, v9
	s_waitcnt lgkmcnt(0)
	v_max_f32_e32 v10, v10, v10
	v_max_f32_e32 v172, v9, v10
	v_sub_f32_e32 v81, v81, v172
	v_exp_f32_e32 v81, v81
	v_pk_add_f32 v[82:83], v[82:83], v[172:173] op_sel_hi:[1,0] neg_lo:[0,1] neg_hi:[0,1]
	v_exp_f32_e32 v82, v82
	v_exp_f32_e32 v83, v83
	v_pk_add_f32 v[144:145], v[144:145], v[172:173] op_sel_hi:[1,0] neg_lo:[0,1] neg_hi:[0,1]
	v_exp_f32_e32 v144, v144
	v_add_f32_e32 v9, v81, v82
	v_add_f32_e32 v9, 0, v9
	v_sub_f32_e32 v8, v8, v172
	v_add_f32_e32 v10, v83, v144
	v_add_f32_e32 v9, v10, v9
	v_exp_f32_e32 v145, v145
	v_pk_add_f32 v[146:147], v[146:147], v[172:173] op_sel_hi:[1,0] neg_lo:[0,1] neg_hi:[0,1]
	v_exp_f32_e32 v146, v146
	s_nop 0
	v_add_f32_e32 v10, v145, v146
	v_add_f32_e32 v9, v10, v9
	v_exp_f32_e32 v147, v147
	v_pk_add_f32 v[148:149], v[148:149], v[172:173] op_sel_hi:[1,0] neg_lo:[0,1] neg_hi:[0,1]
	v_exp_f32_e32 v148, v148
	s_nop 0
	v_add_f32_e32 v10, v147, v148
	v_add_f32_e32 v9, v10, v9
	v_pk_add_f32 v[74:75], v[74:75], v[172:173] op_sel_hi:[1,0] neg_lo:[0,1] neg_hi:[0,1]
	v_exp_f32_e32 v51, v74
	v_pk_add_f32 v[72:73], v[72:73], v[172:173] op_sel_hi:[1,0] neg_lo:[0,1] neg_hi:[0,1]
	v_exp_f32_e32 v72, v72
	s_nop 0
	v_add_f32_e32 v10, v51, v72
	v_add_f32_e32 v9, v10, v9
	v_exp_f32_e32 v74, v75
	v_exp_f32_e32 v73, v73
	s_nop 0
	v_add_f32_e32 v10, v74, v73
	v_add_f32_e32 v9, v10, v9
	v_pk_add_f32 v[78:79], v[78:79], v[172:173] op_sel_hi:[1,0] neg_lo:[0,1] neg_hi:[0,1]
	v_exp_f32_e32 v75, v78
	v_pk_add_f32 v[76:77], v[76:77], v[172:173] op_sel_hi:[1,0] neg_lo:[0,1] neg_hi:[0,1]
	v_exp_f32_e32 v76, v76
	s_nop 0
	v_add_f32_e32 v10, v75, v76
	v_add_f32_e32 v9, v10, v9
	v_exp_f32_e32 v78, v79
	v_exp_f32_e32 v79, v77
	s_nop 0
	v_add_f32_e32 v10, v78, v79
	v_add_f32_e32 v9, v10, v9
	v_pk_add_f32 v[66:67], v[66:67], v[172:173] op_sel_hi:[1,0] neg_lo:[0,1] neg_hi:[0,1]
	v_exp_f32_e32 v66, v66
	v_pk_add_f32 v[64:65], v[64:65], v[172:173] op_sel_hi:[1,0] neg_lo:[0,1] neg_hi:[0,1]
	v_exp_f32_e32 v64, v64
	s_nop 0
	v_add_f32_e32 v10, v66, v64
	v_add_f32_e32 v9, v10, v9
	v_exp_f32_e32 v67, v67
	v_exp_f32_e32 v65, v65
	s_nop 0
	v_add_f32_e32 v10, v67, v65
	v_add_f32_e32 v9, v10, v9
	v_pk_add_f32 v[70:71], v[70:71], v[172:173] op_sel_hi:[1,0] neg_lo:[0,1] neg_hi:[0,1]
	v_exp_f32_e32 v70, v70
	v_pk_add_f32 v[68:69], v[68:69], v[172:173] op_sel_hi:[1,0] neg_lo:[0,1] neg_hi:[0,1]
	v_exp_f32_e32 v77, v68
	s_nop 0
	v_add_f32_e32 v10, v70, v77
	v_add_f32_e32 v9, v10, v9
	v_exp_f32_e32 v71, v71
	v_exp_f32_e32 v69, v69
	s_nop 0
	v_add_f32_e32 v10, v71, v69
	v_add_f32_e32 v9, v10, v9
	v_pk_add_f32 v[58:59], v[58:59], v[172:173] op_sel_hi:[1,0] neg_lo:[0,1] neg_hi:[0,1]
	v_exp_f32_e32 v58, v58
	v_pk_add_f32 v[56:57], v[56:57], v[172:173] op_sel_hi:[1,0] neg_lo:[0,1] neg_hi:[0,1]
	v_exp_f32_e32 v56, v56
	s_nop 0
	v_add_f32_e32 v10, v58, v56
	v_add_f32_e32 v9, v10, v9
	v_exp_f32_e32 v59, v59
	v_exp_f32_e32 v68, v57
	s_nop 0
	v_add_f32_e32 v10, v59, v68
	v_add_f32_e32 v9, v10, v9
	v_pk_add_f32 v[62:63], v[62:63], v[172:173] op_sel_hi:[1,0] neg_lo:[0,1] neg_hi:[0,1]
	v_exp_f32_e32 v62, v62
	v_pk_add_f32 v[60:61], v[60:61], v[172:173] op_sel_hi:[1,0] neg_lo:[0,1] neg_hi:[0,1]
	v_exp_f32_e32 v60, v60
	s_nop 0
	v_add_f32_e32 v10, v62, v60
	v_add_f32_e32 v9, v10, v9
	v_exp_f32_e32 v63, v63
	v_exp_f32_e32 v61, v61
	s_nop 0
	v_add_f32_e32 v10, v63, v61
	v_add_f32_e32 v9, v10, v9
	v_pk_add_f32 v[150:151], v[150:151], v[172:173] op_sel_hi:[1,0] neg_lo:[0,1] neg_hi:[0,1]
	v_exp_f32_e32 v57, v150
	v_pk_add_f32 v[54:55], v[54:55], v[172:173] op_sel_hi:[1,0] neg_lo:[0,1] neg_hi:[0,1]
	v_exp_f32_e32 v55, v55
	s_nop 0
	v_add_f32_e32 v10, v57, v55
	v_add_f32_e32 v9, v10, v9
	v_exp_f32_e32 v54, v54
	v_pk_add_f32 v[52:53], v[52:53], v[172:173] op_sel_hi:[1,0] neg_lo:[0,1] neg_hi:[0,1]
	v_exp_f32_e32 v53, v53
	s_nop 0
	v_add_f32_e32 v10, v54, v53
	v_add_f32_e32 v9, v10, v9
	v_exp_f32_e32 v52, v52
	v_sub_f32_e32 v50, v50, v172
	v_exp_f32_e32 v50, v50
	s_nop 0
	v_add_f32_e32 v10, v52, v50
	v_add_f32_e32 v9, v10, v9
	v_pk_add_f32 v[48:49], v[48:49], v[172:173] op_sel_hi:[1,0] neg_lo:[0,1] neg_hi:[0,1]
	v_exp_f32_e32 v49, v49
	v_exp_f32_e32 v48, v48
	s_nop 0
	v_add_f32_e32 v10, v49, v48
	v_add_f32_e32 v9, v10, v9
	v_pk_add_f32 v[42:43], v[42:43], v[172:173] op_sel_hi:[1,0] neg_lo:[0,1] neg_hi:[0,1]
	v_exp_f32_e32 v42, v42
	v_pk_add_f32 v[40:41], v[40:41], v[172:173] op_sel_hi:[1,0] neg_lo:[0,1] neg_hi:[0,1]
	v_exp_f32_e32 v40, v40
	s_nop 0
	v_add_f32_e32 v10, v42, v40
	v_add_f32_e32 v9, v10, v9
	v_exp_f32_e32 v43, v43
	v_exp_f32_e32 v41, v41
	s_nop 0
	v_add_f32_e32 v10, v43, v41
	v_add_f32_e32 v9, v10, v9
	v_pk_add_f32 v[46:47], v[46:47], v[172:173] op_sel_hi:[1,0] neg_lo:[0,1] neg_hi:[0,1]
	v_exp_f32_e32 v46, v46
	v_pk_add_f32 v[44:45], v[44:45], v[172:173] op_sel_hi:[1,0] neg_lo:[0,1] neg_hi:[0,1]
	v_exp_f32_e32 v44, v44
	s_nop 0
	v_add_f32_e32 v10, v46, v44
	v_add_f32_e32 v9, v10, v9
	v_exp_f32_e32 v47, v47
	v_exp_f32_e32 v45, v45
	s_nop 0
	v_add_f32_e32 v10, v47, v45
	v_add_f32_e32 v9, v10, v9
	v_pk_add_f32 v[34:35], v[34:35], v[172:173] op_sel_hi:[1,0] neg_lo:[0,1] neg_hi:[0,1]
	v_exp_f32_e32 v34, v34
	v_pk_add_f32 v[32:33], v[32:33], v[172:173] op_sel_hi:[1,0] neg_lo:[0,1] neg_hi:[0,1]
	v_exp_f32_e32 v32, v32
	s_nop 0
	v_add_f32_e32 v10, v34, v32
	v_add_f32_e32 v9, v10, v9
	v_exp_f32_e32 v35, v35
	v_exp_f32_e32 v33, v33
	s_nop 0
	v_add_f32_e32 v10, v35, v33
	v_add_f32_e32 v9, v10, v9
	v_pk_add_f32 v[38:39], v[38:39], v[172:173] op_sel_hi:[1,0] neg_lo:[0,1] neg_hi:[0,1]
	v_exp_f32_e32 v38, v38
	v_pk_add_f32 v[36:37], v[36:37], v[172:173] op_sel_hi:[1,0] neg_lo:[0,1] neg_hi:[0,1]
	v_exp_f32_e32 v36, v36
	s_nop 0
	v_add_f32_e32 v10, v38, v36
	v_add_f32_e32 v9, v10, v9
	v_exp_f32_e32 v39, v39
	v_exp_f32_e32 v37, v37
	s_nop 0
	v_add_f32_e32 v10, v39, v37
	v_add_f32_e32 v9, v10, v9
	v_pk_add_f32 v[26:27], v[26:27], v[172:173] op_sel_hi:[1,0] neg_lo:[0,1] neg_hi:[0,1]
	v_exp_f32_e32 v17, v26
	v_pk_add_f32 v[24:25], v[24:25], v[172:173] op_sel_hi:[1,0] neg_lo:[0,1] neg_hi:[0,1]
	v_exp_f32_e32 v19, v24
	v_exp_f32_e32 v16, v27
	v_exp_f32_e32 v18, v25
	s_nop 0
	v_pk_add_f32 v[10:11], v[16:17], v[18:19]
	s_nop 0
	v_add_f32_e32 v9, v11, v9
	v_add_f32_e32 v9, v10, v9
	v_pk_add_f32 v[30:31], v[30:31], v[172:173] op_sel_hi:[1,0] neg_lo:[0,1] neg_hi:[0,1]
	v_exp_f32_e32 v21, v30
	v_pk_add_f32 v[28:29], v[28:29], v[172:173] op_sel_hi:[1,0] neg_lo:[0,1] neg_hi:[0,1]
	v_exp_f32_e32 v23, v28
	v_exp_f32_e32 v20, v31
	v_exp_f32_e32 v22, v29
	v_cvt_pk_bf16_f32 v28, v81, v83
	v_cvt_pk_bf16_f32 v29, v145, v147
	v_cvt_pk_bf16_f32 v30, v82, v144
	v_cvt_pk_bf16_f32 v31, v146, v148
	s_nop 1
	s_nop 0
	v_pk_add_f32 v[10:11], v[20:21], v[22:23]
	s_nop 0
	v_add_f32_e32 v9, v11, v9
	v_add_f32_e32 v15, v10, v9
	v_pk_add_f32 v[12:13], v[12:13], v[172:173] op_sel_hi:[1,0] neg_lo:[0,1] neg_hi:[0,1]
	v_exp_f32_e32 v11, v8
	v_exp_f32_e32 v9, v12
	v_exp_f32_e32 v8, v13
	v_exp_f32_e32 v10, v149
	s_nop 0
	v_pk_add_f32 v[12:13], v[8:9], v[10:11]
	s_nop 0
	v_add_f32_e32 v13, v13, v15
	v_add_f32_e32 v26, v12, v13
	v_sub_f32_e32 v14, v14, v172
	v_exp_f32_e32 v13, v14
	v_exp_f32_e32 v15, v151
	v_sub_f32_e32 v152, v152, v172
	v_sub_f32_e32 v173, v173, v172
	v_exp_f32_e32 v12, v152
	v_exp_f32_e32 v14, v173
	s_nop 0
	v_pk_add_f32 v[24:25], v[12:13], v[14:15]
	s_nop 0
	v_add_f32_e32 v25, v25, v26
	v_add_f32_e32 v24, v24, v25
	ds_bpermute_b32 v25, v114, v24
	v_lshl_add_u32 v26, v80, 1, v118
	ds_read_b128 v[80:83], v26 offset:55296
	s_waitcnt lgkmcnt(1)
	v_add_f32_e32 v24, v24, v25
	ds_bpermute_b32 v25, v117, v24
	s_waitcnt lgkmcnt(0)
	v_add_f32_e32 v24, v24, v25
	v_sub_f32_e32 v25, v143, v172
	v_exp_f32_e32 v25, v25
	s_nop 0
	v_add_f32_e32 v24, v25, v24
	v_add_u32_e32 v25, 0xd800, v26
	ds_read_b128 v[144:147], v25 offset:12544
	ds_read_b128 v[172:175], v25 offset:37632
	ds_read_b128 v[148:151], v25 offset:25088
	v_mfma_f32_16x16x32_bf16 v[80:83], v[80:83], v[28:31], 0
	s_waitcnt lgkmcnt(2)
	v_mfma_f32_16x16x32_bf16 v[144:147], v[144:147], v[28:31], 0
	s_waitcnt lgkmcnt(0)
	v_mfma_f32_16x16x32_bf16 v[148:151], v[148:151], v[28:31], 0
	v_mfma_f32_16x16x32_bf16 v[28:31], v[172:175], v[28:31], 0
	v_cvt_pk_bf16_f32 v172, v51, v74
	v_cvt_pk_bf16_f32 v173, v75, v78
	v_cvt_pk_bf16_f32 v174, v72, v73
	v_cvt_pk_bf16_f32 v175, v76, v79
	s_nop 1
	ds_read_b128 v[72:75], v26 offset:55360
	s_waitcnt lgkmcnt(0)
	v_mfma_f32_16x16x32_bf16 v[72:75], v[72:75], v[172:175], v[80:83]
	s_nop 2
	ds_read_b128 v[78:81], v25 offset:12608
	s_waitcnt lgkmcnt(0)
	v_mfma_f32_16x16x32_bf16 v[78:81], v[78:81], v[172:175], v[144:147]
	s_nop 2
	ds_read_b128 v[144:147], v25 offset:25152
	s_waitcnt lgkmcnt(0)
	v_mfma_f32_16x16x32_bf16 v[144:147], v[144:147], v[172:175], v[148:151]
	s_nop 2
	ds_read_b128 v[148:151], v25 offset:37696
	s_waitcnt lgkmcnt(0)
	v_mfma_f32_16x16x32_bf16 v[28:31], v[148:151], v[172:175], v[28:31]
	v_cvt_pk_bf16_f32 v148, v66, v67
	v_cvt_pk_bf16_f32 v149, v70, v71
	v_cvt_pk_bf16_f32 v150, v64, v65
	v_cvt_pk_bf16_f32 v151, v77, v69
	s_nop 1
	ds_read_b128 v[64:67], v26 offset:55424
	s_waitcnt lgkmcnt(0)
	v_mfma_f32_16x16x32_bf16 v[64:67], v[64:67], v[148:151], v[72:75]
	s_nop 2
	ds_read_b128 v[70:73], v25 offset:12672
	ds_read_b128 v[74:77], v25 offset:25216
	s_waitcnt lgkmcnt(1)
	v_mfma_f32_16x16x32_bf16 v[70:73], v[70:73], v[148:151], v[78:81]
	s_nop 2
	ds_read_b128 v[78:81], v25 offset:37760
	s_waitcnt lgkmcnt(0)
	v_mfma_f32_16x16x32_bf16 v[28:31], v[78:81], v[148:151], v[28:31]
	v_cvt_pk_bf16_f32 v78, v58, v59
	v_cvt_pk_bf16_f32 v79, v62, v63
	v_cvt_pk_bf16_f32 v80, v56, v68
	v_cvt_pk_bf16_f32 v81, v60, v61
	s_nop 1
	ds_read_b128 v[58:61], v26 offset:55488
	s_waitcnt lgkmcnt(0)
	v_mfma_f32_16x16x32_bf16 v[58:61], v[58:61], v[78:81], v[64:67]
	s_nop 2
	ds_read_b128 v[62:65], v25 offset:12736
	ds_read_b128 v[66:69], v25 offset:25280
	s_waitcnt lgkmcnt(1)
	v_mfma_f32_16x16x32_bf16 v[62:65], v[62:65], v[78:81], v[70:73]
	s_nop 2
	ds_read_b128 v[70:73], v25 offset:37824
	s_waitcnt lgkmcnt(0)
	v_mfma_f32_16x16x32_bf16 v[28:31], v[70:73], v[78:81], v[28:31]
	v_cvt_pk_bf16_f32 v70, v57, v54
	v_cvt_pk_bf16_f32 v71, v52, v49
	v_cvt_pk_bf16_f32 v72, v55, v53
	v_cvt_pk_bf16_f32 v73, v50, v48
	s_nop 1
	ds_read_b128 v[48:51], v26 offset:55552
	ds_read_b128 v[52:55], v25 offset:12800
	s_waitcnt lgkmcnt(1)
	v_mfma_f32_16x16x32_bf16 v[48:51], v[48:51], v[70:73], v[58:61]
	s_nop 2
	ds_read_b128 v[56:59], v25 offset:25344
	s_waitcnt lgkmcnt(1)
	v_mfma_f32_16x16x32_bf16 v[52:55], v[52:55], v[70:73], v[62:65]
	s_nop 2
	ds_read_b128 v[60:63], v25 offset:37888
	s_waitcnt lgkmcnt(0)
	v_mfma_f32_16x16x32_bf16 v[28:31], v[60:63], v[70:73], v[28:31]
	v_cvt_pk_bf16_f32 v60, v42, v43
	v_cvt_pk_bf16_f32 v61, v46, v47
	v_cvt_pk_bf16_f32 v62, v40, v41
	v_cvt_pk_bf16_f32 v63, v44, v45
	s_nop 1
	ds_read_b128 v[40:43], v26 offset:55616
	ds_read_b128 v[44:47], v25 offset:12864
	s_waitcnt lgkmcnt(1)
	v_mfma_f32_16x16x32_bf16 v[40:43], v[40:43], v[60:63], v[48:51]
	s_nop 2
	ds_read_b128 v[48:51], v25 offset:25408
	s_waitcnt lgkmcnt(1)
	v_mfma_f32_16x16x32_bf16 v[44:47], v[44:47], v[60:63], v[52:55]
	s_nop 2
	ds_read_b128 v[52:55], v25 offset:37952
	s_waitcnt lgkmcnt(0)
	v_mfma_f32_16x16x32_bf16 v[28:31], v[52:55], v[60:63], v[28:31]
	v_cvt_pk_bf16_f32 v52, v34, v35
	v_cvt_pk_bf16_f32 v53, v38, v39
	v_cvt_pk_bf16_f32 v54, v32, v33
	v_cvt_pk_bf16_f32 v55, v36, v37
	s_nop 1
	ds_read_b128 v[32:35], v26 offset:55680
	ds_read_b128 v[36:39], v25 offset:12928
	s_waitcnt lgkmcnt(1)
	v_mfma_f32_16x16x32_bf16 v[32:35], v[32:35], v[52:55], v[40:43]
	s_nop 2
	ds_read_b128 v[40:43], v25 offset:25472
	s_waitcnt lgkmcnt(1)
	v_mfma_f32_16x16x32_bf16 v[36:39], v[36:39], v[52:55], v[44:47]
	s_nop 2
	ds_read_b128 v[44:47], v25 offset:38016
	s_waitcnt lgkmcnt(0)
	v_mfma_f32_16x16x32_bf16 v[28:31], v[44:47], v[52:55], v[28:31]
	v_cvt_pk_bf16_f32 v44, v17, v16
	v_cvt_pk_bf16_f32 v45, v21, v20
	v_cvt_pk_bf16_f32 v46, v19, v18
	v_cvt_pk_bf16_f32 v47, v23, v22
	s_nop 1
	ds_read_b128 v[16:19], v26 offset:55744
	ds_read_b128 v[20:23], v25 offset:12992
	s_waitcnt lgkmcnt(1)
	v_mfma_f32_16x16x32_bf16 v[16:19], v[16:19], v[44:47], v[32:35]
	s_nop 2
	ds_read_b128 v[32:35], v25 offset:25536
	s_waitcnt lgkmcnt(1)
	v_mfma_f32_16x16x32_bf16 v[20:23], v[20:23], v[44:47], v[36:39]
	s_nop 2
	ds_read_b128 v[36:39], v25 offset:38080
	s_waitcnt lgkmcnt(0)
	v_mfma_f32_16x16x32_bf16 v[28:31], v[36:39], v[44:47], v[28:31]
	v_cvt_pk_bf16_f32 v36, v9, v8
	v_cvt_pk_bf16_f32 v37, v13, v12
	v_cvt_pk_bf16_f32 v38, v11, v10
	v_cvt_pk_bf16_f32 v39, v15, v14
	s_nop 1
	ds_read_b128 v[8:11], v26 offset:55808
	ds_read_b128 v[12:15], v25 offset:13056
	s_waitcnt lgkmcnt(1)
	v_mfma_f32_16x16x32_bf16 v[8:11], v[8:11], v[36:39], v[16:19]
	s_nop 2
	ds_read_b128 v[16:19], v25 offset:25600
	s_waitcnt lgkmcnt(1)
	v_mfma_f32_16x16x32_bf16 v[12:15], v[12:15], v[36:39], v[20:23]
	s_nop 2
	ds_read_b128 v[20:23], v25 offset:38144
	v_div_scale_f32 v25, s[0:1], v24, v24, 1.0
	v_mfma_f32_16x16x32_bf16 v[74:77], v[74:77], v[148:151], v[144:147]
	v_rcp_f32_e32 v26, v25
	s_mov_b32 s0, 0x1b400000
	v_fma_f32 v27, -v25, v26, 1.0
	v_mfma_f32_16x16x32_bf16 v[66:69], v[66:69], v[78:81], v[74:77]
	v_fmac_f32_e32 v26, v27, v26
	v_div_scale_f32 v27, vcc, 1.0, v24, 1.0
	s_waitcnt lgkmcnt(0)
	v_mfma_f32_16x16x32_bf16 v[20:23], v[20:23], v[36:39], v[28:31]
	s_nop 2
	v_mul_f32_e32 v28, v27, v26
	v_fma_f32 v29, -v25, v28, v27
	v_mfma_f32_16x16x32_bf16 v[56:59], v[56:59], v[70:73], v[66:69]
	v_fmac_f32_e32 v28, v29, v26
	v_fma_f32 v25, -v25, v28, v27
	v_div_fmas_f32 v25, v25, v26, v28
	v_div_fixup_f32 v24, v25, v24, 1.0
	v_mfma_f32_16x16x32_bf16 v[48:51], v[48:51], v[60:63], v[56:59]
	v_mul_f32_e64 v8, v24, v8
	v_mul_f32_e64 v9, v24, v9
	v_pk_mul_f32 v[10:11], v[24:25], v[10:11] op_sel_hi:[0,1]
	v_cvt_pk_bf16_f32 v8, v8, v9
	s_nop 3
	v_mfma_f32_16x16x32_bf16 v[40:43], v[40:43], v[52:55], v[48:51]
	v_cvt_pk_bf16_f32 v9, v10, v11
	v_lshl_add_u64 v[26:27], v[110:111], 0, s[16:17]
	v_add_co_u32_e32 v10, vcc, s0, v26
	s_nop 5
	v_mfma_f32_16x16x32_bf16 v[32:35], v[32:35], v[44:47], v[40:43]
	s_nop 0
	v_addc_co_u32_e32 v11, vcc, 0, v27, vcc
	v_pk_mul_f32 v[12:13], v[24:25], v[12:13] op_sel_hi:[0,1]
	global_store_dwordx2 v[10:11], v[8:9], off
	v_pk_mul_f32 v[8:9], v[24:25], v[14:15] op_sel_hi:[0,1]
	v_cvt_pk_bf16_f32 v12, v12, v13
	s_nop 3
	v_mfma_f32_16x16x32_bf16 v[16:19], v[16:19], v[36:39], v[32:35]
	v_cvt_pk_bf16_f32 v13, v8, v9
	global_store_dwordx2 v[10:11], v[12:13], off offset:32
	s_nop 5
	v_pk_mul_f32 v[12:13], v[24:25], v[16:17] op_sel_hi:[0,1]
	v_cvt_pk_bf16_f32 v12, v12, v13
	v_pk_mul_f32 v[8:9], v[24:25], v[18:19] op_sel_hi:[0,1]
	v_cvt_pk_bf16_f32 v13, v8, v9
	global_store_dwordx2 v[10:11], v[12:13], off offset:64
	v_pk_mul_f32 v[12:13], v[24:25], v[20:21] op_sel_hi:[0,1]
	v_cvt_pk_bf16_f32 v12, v12, v13
	v_pk_mul_f32 v[8:9], v[24:25], v[22:23] op_sel_hi:[0,1]
	v_cvt_pk_bf16_f32 v13, v8, v9
	s_add_u32 s16, s16, 0x4000
	global_store_dwordx2 v[10:11], v[12:13], off offset:96
	s_addc_u32 s17, s17, 0
	s_add_i32 s18, s18, 0xd000
	s_add_i32 s19, s19, 16
	s_mov_b64 s[0:1], 0x400
	s_waitcnt vmcnt(4)
	v_mov_b64_e32 v[10:11], v[6:7]
	v_lshl_add_u64 v[108:109], v[108:109], 0, s[0:1]
	s_cmp_eq_u32 s16, 0x10000
	v_mov_b64_e32 v[8:9], v[4:5]
	s_cbranch_scc1 .LBB0_564
.LBB0_579:
	s_cmpk_lg_u32 s16, 0xc000
	s_cselect_b32 s8, s18, 0x27000
	v_mov_b64_e32 v[82:83], v[2:3]
	v_lshl_add_u64 v[4:5], s[8:9], 1, v[106:107]
	v_mov_b64_e32 v[80:81], v[0:1]
	global_load_dwordx4 v[0:3], v[4:5], off
	s_nop 0
	global_load_dwordx4 v[4:7], v[4:5], off offset:64
	v_lshlrev_b32_e32 v13, 16, v81
	v_lshlrev_b32_e32 v12, 16, v80
	v_and_b32_e32 v15, 0xffff0000, v81
	v_and_b32_e32 v14, 0xffff0000, v80
	v_and_b32_e32 v17, 0xffff0000, v82
	v_lshlrev_b32_e32 v16, 16, v82
	v_and_b32_e32 v19, 0xffff0000, v83
	v_lshlrev_b32_e32 v18, 16, v83
	ds_bpermute_b32 v26, v114, v12
	ds_bpermute_b32 v24, v114, v14
	ds_bpermute_b32 v27, v114, v13
	ds_bpermute_b32 v25, v114, v15
	ds_bpermute_b32 v22, v114, v16
	ds_bpermute_b32 v23, v114, v17
	ds_bpermute_b32 v20, v114, v18
	ds_bpermute_b32 v21, v114, v19
	s_and_saveexec_b64 s[0:1], s[48:49]
	s_cbranch_execz .LBB0_581
	s_waitcnt lgkmcnt(4)
	v_pk_mul_f32 v[24:25], v[90:91], v[24:25]
	s_waitcnt lgkmcnt(2)
	v_pk_mul_f32 v[22:23], v[90:91], v[22:23]
	s_waitcnt lgkmcnt(0)
	v_pk_mul_f32 v[20:21], v[90:91], v[20:21]
	v_pk_mul_f32 v[26:27], v[90:91], v[26:27]
	v_mov_b32_e32 v34, v181
	v_mov_b32_e32 v35, v183
	v_mov_b32_e32 v46, v180
	v_mov_b32_e32 v47, v182
	v_mov_b32_e32 v30, v177
	v_mov_b32_e32 v31, v179
	v_mov_b32_e32 v44, v176
	v_mov_b32_e32 v45, v178
	v_pk_mul_f32 v[22:23], v[22:23], v[184:185]
	v_pk_mul_f32 v[20:21], v[20:21], v[186:187]
	v_pk_mul_f32 v[24:25], v[24:25], v[34:35]
	v_pk_mul_f32 v[26:27], v[26:27], v[46:47]
	v_pk_fma_f32 v[16:17], v[188:189], v[16:17], v[22:23]
	v_pk_fma_f32 v[18:19], v[190:191], v[18:19], v[20:21]
	v_pk_fma_f32 v[14:15], v[30:31], v[14:15], v[24:25]
	v_pk_fma_f32 v[12:13], v[44:45], v[12:13], v[26:27]
	global_load_dwordx4 v[176:179], v[108:109], off offset:1024
	global_load_dwordx4 v[180:183], v[108:109], off offset:1056
	global_load_dwordx4 v[184:187], v[108:109], off offset:1072
	global_load_dwordx4 v[188:191], v[108:109], off offset:1040
	v_cvt_pk_bf16_f32 v82, v16, v17
	v_cvt_pk_bf16_f32 v81, v13, v15
	v_cvt_pk_bf16_f32 v80, v12, v14
	v_cvt_pk_bf16_f32 v83, v18, v19
